# grid barriers: L1 invalidate issued at arrival (overlaps the spin / the L2 writeback) instead of after the release is observed
# speedup vs baseline: 1.0118x; 1.0118x over previous
.LBB0_123:
	s_or_b64 exec, exec, s[8:9]
	v_cvt_f32_u32_e32 v4, v2
	s_waitcnt vmcnt(0)
	v_readfirstlane_b32 s3, v3
	v_sub_u32_e32 v3, 0, v2
	v_rcp_iflag_f32_e32 v4, v4
	v_add_u32_e32 v5, s3, v1
	v_mul_f32_e32 v4, 0x4f7ffffe, v4
	v_cvt_u32_f32_e32 v4, v4
	v_mul_lo_u32 v1, v3, v4
	v_mul_hi_u32 v1, v4, v1
	v_add_u32_e32 v1, v4, v1
	v_mul_hi_u32 v1, v5, v1
	v_mul_lo_u32 v3, v1, v2
	v_sub_u32_e32 v3, v5, v3
	v_add_u32_e32 v4, 1, v1
	v_cmp_ge_u32_e32 vcc, v3, v2
	s_nop 1
	v_cndmask_b32_e32 v1, v1, v4, vcc
	v_sub_u32_e32 v4, v3, v2
	v_cndmask_b32_e32 v3, v3, v4, vcc
	v_add_u32_e32 v4, 1, v1
	v_cmp_ge_u32_e32 vcc, v3, v2
	v_add_u32_e32 v3, 1, v5
	s_nop 0
	v_cndmask_b32_e32 v1, v1, v4, vcc
	v_mul_lo_u32 v4, v2, v1
	v_add_u32_e32 v2, v4, v2
	v_cmp_ne_u32_e32 vcc, v3, v2
	s_and_saveexec_b64 s[6:7], vcc
	s_xor_b64 s[6:7], exec, s[6:7]
	s_cbranch_execz .LBB0_137
	s_waitcnt lgkmcnt(0)
	v_mov_b32_e32 v0, 0x2000
	buffer_inv sc1
	global_load_dword v0, v0, s[4:5] offset:1024 sc1
	s_add_u32 s12, s4, 0x2400
	s_addc_u32 s13, s5, 0
	s_waitcnt vmcnt(0)
	v_cmp_eq_u32_e32 vcc, v0, v1
	s_and_saveexec_b64 s[8:9], vcc
	s_cbranch_execz .LBB0_136
	s_add_u32 s10, s24, 0x18200
	s_addc_u32 s11, s25, 0
	s_mov_b32 s3, 1
	s_mov_b64 s[16:17], 0
	v_mov_b32_e32 v0, 0
	s_branch .LBB0_127

.LBB0_136:
	s_or_b64 exec, exec, s[8:9]
	s_waitcnt vmcnt(0)
	s_waitcnt vmcnt(0)
.LBB0_137:
	s_andn2_saveexec_b64 s[6:7], s[6:7]
	s_cbranch_execz .LBB0_157
	s_mov_b64 s[6:7], exec
	buffer_wbl2 sc1
	buffer_inv sc1
	s_waitcnt lgkmcnt(0)
	s_waitcnt vmcnt(0)
	v_mbcnt_lo_u32_b32 v1, s6, 0
	v_mbcnt_hi_u32_b32 v1, s7, v1
	v_cmp_eq_u32_e32 vcc, 0, v1
	s_and_saveexec_b64 s[8:9], vcc
	s_cbranch_execz .LBB0_140
	s_bcnt1_i32_b64 s3, s[6:7]
	v_mov_b32_e32 v2, 0x1b000
	v_mov_b32_e32 v3, s3
	global_atomic_add v2, v2, v3, s[24:25] offset:1024 sc0

.LBB0_154:
	s_or_b64 exec, exec, s[6:7]
	s_mov_b64 s[6:7], exec
	v_mbcnt_lo_u32_b32 v0, s6, 0
	v_mbcnt_hi_u32_b32 v0, s7, v0
	v_cmp_eq_u32_e32 vcc, 0, v0
	s_waitcnt vmcnt(0)
	s_and_saveexec_b64 s[8:9], vcc
	s_cbranch_execz .LBB0_156
	s_bcnt1_i32_b64 s3, s[6:7]
	v_mov_b32_e32 v0, 0x2000
	v_mov_b32_e32 v1, s3
	global_atomic_add v0, v1, s[4:5] offset:1024

.LBB0_246:
	s_or_b64 exec, exec, s[8:9]
	v_cvt_f32_u32_e32 v4, v2
	s_waitcnt vmcnt(0)
	v_readfirstlane_b32 s6, v3
	v_sub_u32_e32 v3, 0, v2
	v_rcp_iflag_f32_e32 v4, v4
	v_add_u32_e32 v5, s6, v1
	v_mul_f32_e32 v4, 0x4f7ffffe, v4
	v_cvt_u32_f32_e32 v4, v4
	v_mul_lo_u32 v1, v3, v4
	v_mul_hi_u32 v1, v4, v1
	v_add_u32_e32 v1, v4, v1
	v_mul_hi_u32 v1, v5, v1
	v_mul_lo_u32 v3, v1, v2
	v_sub_u32_e32 v3, v5, v3
	v_add_u32_e32 v4, 1, v1
	v_cmp_ge_u32_e32 vcc, v3, v2
	s_nop 1
	v_cndmask_b32_e32 v1, v1, v4, vcc
	v_sub_u32_e32 v4, v3, v2
	v_cndmask_b32_e32 v3, v3, v4, vcc
	v_add_u32_e32 v4, 1, v1
	v_cmp_ge_u32_e32 vcc, v3, v2
	v_add_u32_e32 v3, 1, v5
	s_nop 0
	v_cndmask_b32_e32 v1, v1, v4, vcc
	v_mul_lo_u32 v4, v2, v1
	v_add_u32_e32 v2, v4, v2
	v_cmp_ne_u32_e32 vcc, v3, v2
	s_and_saveexec_b64 s[6:7], vcc
	s_xor_b64 s[6:7], exec, s[6:7]
	s_cbranch_execz .LBB0_260
	s_waitcnt lgkmcnt(0)
	v_mov_b32_e32 v0, 0x2000
	buffer_inv sc1
	global_load_dword v0, v0, s[4:5] offset:1024 sc1
	s_add_u32 s12, s4, 0x2400
	s_addc_u32 s13, s5, 0
	s_waitcnt vmcnt(0)
	v_cmp_eq_u32_e32 vcc, v0, v1
	s_and_saveexec_b64 s[8:9], vcc
	s_cbranch_execz .LBB0_259
	s_add_u32 s10, s24, 0x18200
	s_addc_u32 s11, s25, 0
	s_mov_b32 s39, 1
	s_mov_b64 s[48:49], 0
	v_mov_b32_e32 v0, 0
	s_branch .LBB0_250

.LBB0_260:
	s_andn2_saveexec_b64 s[6:7], s[6:7]
	s_cbranch_execz .LBB0_280
	s_mov_b64 s[8:9], exec
	buffer_wbl2 sc1
	buffer_inv sc1
	s_waitcnt lgkmcnt(0)
	s_waitcnt vmcnt(0)
	v_mbcnt_lo_u32_b32 v1, s8, 0
	v_mbcnt_hi_u32_b32 v1, s9, v1
	v_cmp_eq_u32_e32 vcc, 0, v1
	s_and_saveexec_b64 s[10:11], vcc
	s_cbranch_execz .LBB0_263
	s_bcnt1_i32_b64 s8, s[8:9]
	v_mov_b32_e32 v2, 0x1b000
	v_mov_b32_e32 v3, s8
	global_atomic_add v2, v2, v3, s[24:25] offset:1024 sc0

.LBB0_277:
	s_or_b64 exec, exec, s[8:9]
	s_mov_b64 s[8:9], exec
	v_mbcnt_lo_u32_b32 v0, s8, 0
	v_mbcnt_hi_u32_b32 v0, s9, v0
	v_cmp_eq_u32_e32 vcc, 0, v0
	s_waitcnt vmcnt(0)
	s_and_saveexec_b64 s[10:11], vcc
	s_cbranch_execz .LBB0_279
	s_bcnt1_i32_b64 s8, s[8:9]
	v_mov_b32_e32 v0, 0x2000
	v_mov_b32_e32 v1, s8
	global_atomic_add v0, v1, s[4:5] offset:1024

.LBB0_379:
	s_or_b64 exec, exec, s[8:9]
	v_cvt_f32_u32_e32 v4, v2
	s_waitcnt vmcnt(0)
	v_readfirstlane_b32 s6, v3
	v_sub_u32_e32 v3, 0, v2
	v_rcp_iflag_f32_e32 v4, v4
	v_add_u32_e32 v5, s6, v1
	v_mul_f32_e32 v4, 0x4f7ffffe, v4
	v_cvt_u32_f32_e32 v4, v4
	v_mul_lo_u32 v1, v3, v4
	v_mul_hi_u32 v1, v4, v1
	v_add_u32_e32 v1, v4, v1
	v_mul_hi_u32 v1, v5, v1
	v_mul_lo_u32 v3, v1, v2
	v_sub_u32_e32 v3, v5, v3
	v_add_u32_e32 v4, 1, v1
	v_cmp_ge_u32_e32 vcc, v3, v2
	s_nop 1
	v_cndmask_b32_e32 v1, v1, v4, vcc
	v_sub_u32_e32 v4, v3, v2
	v_cndmask_b32_e32 v3, v3, v4, vcc
	v_add_u32_e32 v4, 1, v1
	v_cmp_ge_u32_e32 vcc, v3, v2
	v_add_u32_e32 v3, 1, v5
	s_nop 0
	v_cndmask_b32_e32 v1, v1, v4, vcc
	v_mul_lo_u32 v4, v2, v1
	v_add_u32_e32 v2, v4, v2
	v_cmp_ne_u32_e32 vcc, v3, v2
	s_and_saveexec_b64 s[6:7], vcc
	s_xor_b64 s[6:7], exec, s[6:7]
	s_cbranch_execz .LBB0_393
	s_waitcnt lgkmcnt(0)
	v_mov_b32_e32 v0, 0x2000
	buffer_inv sc1
	global_load_dword v0, v0, s[4:5] offset:1024 sc1
	s_add_u32 s18, s4, 0x2400
	s_addc_u32 s19, s5, 0
	s_waitcnt vmcnt(0)
	v_cmp_eq_u32_e32 vcc, v0, v1
	s_and_saveexec_b64 s[8:9], vcc
	s_cbranch_execz .LBB0_392
	s_add_u32 s10, s24, 0x18200
	s_addc_u32 s11, s25, 0
	s_mov_b32 s39, 1
	s_mov_b64 s[40:41], 0
	v_mov_b32_e32 v0, 0
	s_branch .LBB0_383

.LBB0_561:
	s_or_b64 exec, exec, s[12:13]
	v_cvt_f32_u32_e32 v4, v2
	s_waitcnt vmcnt(0)
	v_readfirstlane_b32 s10, v3
	v_sub_u32_e32 v3, 0, v2
	v_rcp_iflag_f32_e32 v4, v4
	v_add_u32_e32 v5, s10, v1
	v_mul_f32_e32 v4, 0x4f7ffffe, v4
	v_cvt_u32_f32_e32 v4, v4
	v_mul_lo_u32 v1, v3, v4
	v_mul_hi_u32 v1, v4, v1
	v_add_u32_e32 v1, v4, v1
	v_mul_hi_u32 v1, v5, v1
	v_mul_lo_u32 v3, v1, v2
	v_sub_u32_e32 v3, v5, v3
	v_add_u32_e32 v4, 1, v1
	v_cmp_ge_u32_e32 vcc, v3, v2
	s_nop 1
	v_cndmask_b32_e32 v1, v1, v4, vcc
	v_sub_u32_e32 v4, v3, v2
	v_cndmask_b32_e32 v3, v3, v4, vcc
	v_add_u32_e32 v4, 1, v1
	v_cmp_ge_u32_e32 vcc, v3, v2
	v_add_u32_e32 v3, 1, v5
	s_nop 0
	v_cndmask_b32_e32 v1, v1, v4, vcc
	v_mul_lo_u32 v4, v2, v1
	v_add_u32_e32 v2, v4, v2
	v_cmp_ne_u32_e32 vcc, v3, v2
	s_and_saveexec_b64 s[10:11], vcc
	s_xor_b64 s[10:11], exec, s[10:11]
	s_cbranch_execz .LBB0_575
	s_waitcnt lgkmcnt(0)
	v_mov_b32_e32 v0, 0x2000
	buffer_inv sc1
	global_load_dword v0, v0, s[8:9] offset:1024 sc1
	s_add_u32 s40, s8, 0x2400
	s_addc_u32 s41, s9, 0
	s_waitcnt vmcnt(0)
	v_cmp_eq_u32_e32 vcc, v0, v1
	s_and_saveexec_b64 s[12:13], vcc
	s_cbranch_execz .LBB0_574
	s_add_u32 s18, s24, 0x18200
	s_addc_u32 s19, s25, 0
	s_mov_b32 s39, 1
	s_mov_b64 s[42:43], 0
	v_mov_b32_e32 v0, 0
	s_branch .LBB0_565

.LBB0_574:
	s_or_b64 exec, exec, s[12:13]
	s_waitcnt vmcnt(0)
	s_waitcnt vmcnt(0)
.LBB0_575:
	s_andn2_saveexec_b64 s[10:11], s[10:11]
	s_cbranch_execz .LBB0_595
	s_mov_b64 s[10:11], exec
	buffer_wbl2 sc1
	buffer_inv sc1
	s_waitcnt lgkmcnt(0)
	s_waitcnt vmcnt(0)
	v_mbcnt_lo_u32_b32 v1, s10, 0
	v_mbcnt_hi_u32_b32 v1, s11, v1
	v_cmp_eq_u32_e32 vcc, 0, v1
	s_and_saveexec_b64 s[12:13], vcc
	s_cbranch_execz .LBB0_578
	s_bcnt1_i32_b64 s10, s[10:11]
	v_mov_b32_e32 v2, 0x1b000
	v_mov_b32_e32 v3, s10
	global_atomic_add v2, v2, v3, s[24:25] offset:1024 sc0

.LBB0_592:
	s_or_b64 exec, exec, s[10:11]
	s_mov_b64 s[10:11], exec
	v_mbcnt_lo_u32_b32 v0, s10, 0
	v_mbcnt_hi_u32_b32 v0, s11, v0
	v_cmp_eq_u32_e32 vcc, 0, v0
	s_waitcnt vmcnt(0)
	s_and_saveexec_b64 s[12:13], vcc
	s_cbranch_execz .LBB0_594
	s_bcnt1_i32_b64 s10, s[10:11]
	v_mov_b32_e32 v0, 0x2000
	v_mov_b32_e32 v1, s10
	global_atomic_add v0, v1, s[8:9] offset:1024

.LBB0_616:
	s_or_b64 exec, exec, s[8:9]
	v_cvt_f32_u32_e32 v4, v2
	s_waitcnt vmcnt(0)
	v_readfirstlane_b32 s6, v3
	v_sub_u32_e32 v3, 0, v2
	v_rcp_iflag_f32_e32 v4, v4
	v_add_u32_e32 v5, s6, v1
	v_mul_f32_e32 v4, 0x4f7ffffe, v4
	v_cvt_u32_f32_e32 v4, v4
	v_mul_lo_u32 v1, v3, v4
	v_mul_hi_u32 v1, v4, v1
	v_add_u32_e32 v1, v4, v1
	v_mul_hi_u32 v1, v5, v1
	v_mul_lo_u32 v3, v1, v2
	v_sub_u32_e32 v3, v5, v3
	v_add_u32_e32 v4, 1, v1
	v_cmp_ge_u32_e32 vcc, v3, v2
	s_nop 1
	v_cndmask_b32_e32 v1, v1, v4, vcc
	v_sub_u32_e32 v4, v3, v2
	v_cndmask_b32_e32 v3, v3, v4, vcc
	v_add_u32_e32 v4, 1, v1
	v_cmp_ge_u32_e32 vcc, v3, v2
	v_add_u32_e32 v3, 1, v5
	s_nop 0
	v_cndmask_b32_e32 v1, v1, v4, vcc
	v_mul_lo_u32 v4, v2, v1
	v_add_u32_e32 v2, v4, v2
	v_cmp_ne_u32_e32 vcc, v3, v2
	s_and_saveexec_b64 s[6:7], vcc
	s_xor_b64 s[6:7], exec, s[6:7]
	s_cbranch_execz .LBB0_630
	s_waitcnt lgkmcnt(0)
	v_mov_b32_e32 v0, 0x2000
	buffer_inv sc1
	global_load_dword v0, v0, s[4:5] offset:1024 sc1
	s_add_u32 s12, s4, 0x2400
	s_addc_u32 s13, s5, 0
	s_waitcnt vmcnt(0)
	v_cmp_eq_u32_e32 vcc, v0, v1
	s_and_saveexec_b64 s[8:9], vcc
	s_cbranch_execz .LBB0_629
	s_add_u32 s10, s24, 0x18200
	s_addc_u32 s11, s25, 0
	s_mov_b32 s27, 1
	s_mov_b64 s[14:15], 0
	v_mov_b32_e32 v0, 0
	s_branch .LBB0_620

.LBB0_630:
	s_andn2_saveexec_b64 s[6:7], s[6:7]
	s_cbranch_execz .LBB0_650
	s_mov_b64 s[6:7], exec
	buffer_wbl2 sc1
	buffer_inv sc1
	s_waitcnt lgkmcnt(0)
	s_waitcnt vmcnt(0)
	v_mbcnt_lo_u32_b32 v1, s6, 0
	v_mbcnt_hi_u32_b32 v1, s7, v1
	v_cmp_eq_u32_e32 vcc, 0, v1
	s_and_saveexec_b64 s[8:9], vcc
	s_cbranch_execz .LBB0_633
	s_bcnt1_i32_b64 s6, s[6:7]
	v_mov_b32_e32 v2, 0x1b000
	v_mov_b32_e32 v3, s6
	global_atomic_add v2, v2, v3, s[24:25] offset:1024 sc0

.LBB0_647:
	s_or_b64 exec, exec, s[6:7]
	s_mov_b64 s[6:7], exec
	v_mbcnt_lo_u32_b32 v0, s6, 0
	v_mbcnt_hi_u32_b32 v0, s7, v0
	v_cmp_eq_u32_e32 vcc, 0, v0
	s_waitcnt vmcnt(0)
	s_and_saveexec_b64 s[8:9], vcc
	s_cbranch_execz .LBB0_649
	s_bcnt1_i32_b64 s6, s[6:7]
	v_mov_b32_e32 v0, 0x2000
	v_mov_b32_e32 v1, s6
	global_atomic_add v0, v1, s[4:5] offset:1024
